# attention: K/V staging block moved from the end to the start of the softmax segment
# baseline (speedup 1.0000x reference)
; template <int R> __device__ __forceinline__ void bias_r(f32x16& p0, f32x16& p1, float dq, float nslope) {
;   constexpr int C0 = (R & 3) + 8 * (R >> 2);
;   float x0, x1, a0 = p0[R], a1 = p1[R];
;   asm("v_sub_f32_e32 %0, %1, %2" : "=v"(x0) : "n"(__builtin_bit_cast(int, (float)C0)), "v"(dq));
;   asm("v_sub_f32_e32 %0, %1, %2" : "=v"(x1) : "n"(__builtin_bit_cast(int, (float)(C0 + 32))), "v"(dq));
;   asm("v_fma_f32 %0, %1, |%2|, %0" : "+v"(a0) : "v"(nslope), "v"(x0));
;   asm("v_fma_f32 %0, %1, |%2|, %0" : "+v"(a1) : "v"(nslope), "v"(x1));
;   p0[R] = a0; p1[R] = a1;
;   if constexpr (R < 15) bias_r<R + 1>(p0, p1, dq, nslope);
; }
.LBB0_366:
	s_add_i32 s72, s22, s46
	s_cmp_lt_i32 s46, s23
	s_cselect_b32 s14, s72, s39
	s_lshl_b32 s14, s14, 6
	v_cvt_f32_i32_e32 v0, s14
	s_barrier
	v_sub_f32_e32 v0, v192, v0
	v_sub_f32_e32 v14, 0, v0
	v_sub_f32_e32 v15, 0x42000000, v0
	s_nop 0
	v_fma_f32 v98, v81, |v14|, v98
	v_sub_f32_e32 v14, 0x3f800000, v0
	v_fma_f32 v114, v81, |v15|, v114
	v_sub_f32_e32 v15, 0x42040000, v0
	s_nop 0
	v_fma_f32 v99, v81, |v14|, v99
	v_sub_f32_e32 v14, 0x40000000, v0
	v_fma_f32 v115, v81, |v15|, v115
	v_sub_f32_e32 v15, 0x42080000, v0
	s_nop 0
	v_fma_f32 v100, v81, |v14|, v100
	v_sub_f32_e32 v14, 0x40400000, v0
	v_fma_f32 v116, v81, |v15|, v116
	v_sub_f32_e32 v15, 0x420c0000, v0
	s_nop 0
	v_fma_f32 v101, v81, |v14|, v101
	v_sub_f32_e32 v14, 0x41000000, v0
	v_fma_f32 v117, v81, |v15|, v117
	v_sub_f32_e32 v15, 0x42200000, v0
	s_nop 0
	v_fma_f32 v102, v81, |v14|, v102
	v_sub_f32_e32 v14, 0x41100000, v0
	v_fma_f32 v118, v81, |v15|, v118
	v_sub_f32_e32 v15, 0x42240000, v0
	s_nop 0
	v_fma_f32 v103, v81, |v14|, v103
	v_sub_f32_e32 v14, 0x41200000, v0
	v_fma_f32 v119, v81, |v15|, v119
	v_sub_f32_e32 v15, 0x42280000, v0
	s_nop 0
	v_fma_f32 v104, v81, |v14|, v104
	v_sub_f32_e32 v14, 0x41300000, v0
	v_fma_f32 v120, v81, |v15|, v120
	v_sub_f32_e32 v15, 0x422c0000, v0
	s_nop 0
	v_fma_f32 v105, v81, |v14|, v105
	v_sub_f32_e32 v14, 0x41800000, v0
	v_fma_f32 v121, v81, |v15|, v121
	v_sub_f32_e32 v15, 0x42400000, v0
	s_nop 0
	v_fma_f32 v106, v81, |v14|, v106
	v_sub_f32_e32 v14, 0x41880000, v0
	v_fma_f32 v122, v81, |v15|, v122
	v_sub_f32_e32 v15, 0x42440000, v0
	s_nop 0
	v_fma_f32 v107, v81, |v14|, v107
	v_sub_f32_e32 v14, 0x41900000, v0
	v_fma_f32 v123, v81, |v15|, v123
	v_sub_f32_e32 v15, 0x42480000, v0
	s_nop 0
	v_fma_f32 v108, v81, |v14|, v108
	v_sub_f32_e32 v14, 0x41980000, v0
	v_fma_f32 v124, v81, |v15|, v124
	v_sub_f32_e32 v15, 0x424c0000, v0
	s_nop 0
	v_fma_f32 v109, v81, |v14|, v109
	v_sub_f32_e32 v14, 0x41c00000, v0
	v_fma_f32 v125, v81, |v15|, v125
	v_sub_f32_e32 v15, 0x42600000, v0
	s_nop 0
	v_fma_f32 v110, v81, |v14|, v110
	v_sub_f32_e32 v14, 0x41c80000, v0
	v_fma_f32 v126, v81, |v15|, v126
	v_sub_f32_e32 v15, 0x42640000, v0
	s_nop 0
	v_fma_f32 v111, v81, |v14|, v111
	v_sub_f32_e32 v14, 0x41d00000, v0
	v_fma_f32 v127, v81, |v15|, v127
	v_sub_f32_e32 v15, 0x42680000, v0
	s_nop 0
	v_fma_f32 v112, v81, |v14|, v112
	v_sub_f32_e32 v14, 0x41d80000, v0
	v_sub_f32_e32 v0, 0x426c0000, v0
	v_fma_f32 v128, v81, |v15|, v128
	s_nop 0
	v_fma_f32 v113, v81, |v14|, v113
	v_fma_f32 v129, v81, |v0|, v129
.Lafter_bias_0:
	s_add_i32 s47, s46, 2
	s_and_b64 s[16:17], exec, s[12:13]
	s_cselect_b32 s16, s46, s47
	s_cmp_gt_i32 s16, s11
	s_cbranch_scc1 .Lstg0_mid
	s_waitcnt vmcnt(3)
	ds_write_b128 v199, v[146:149]
	s_waitcnt vmcnt(2)
	ds_write_b128 v200, v[150:153] offset:4096
	s_waitcnt vmcnt(1)
	ds_write_b128 v201, v[154:157] offset:8192
	s_waitcnt vmcnt(0)
	ds_write_b128 v202, v[158:161] offset:12288
.Lstg0_mid:
	s_cmp_ge_i32 s16, s11
	s_cbranch_scc1 .Lstg0_end
	s_or_b32 s16, s16, 1
	s_add_i32 s17, s16, s22
	s_sub_i32 s33, s38, s16
	s_cmp_lt_i32 s16, s23
	s_cselect_b32 s16, s17, s33
	s_lshl_b32 s16, s16, 6
	s_ashr_i32 s17, s16, 31
	s_lshl_b64 s[74:75], s[16:17], 8
	v_lshl_add_u64 v[204:205], v[170:171], 0, s[74:75]
	s_or_b32 s74, s16, 16
	s_ashr_i32 s75, s74, 31
	s_lshl_b64 s[74:75], s[74:75], 8
	v_lshl_add_u64 v[206:207], v[170:171], 0, s[74:75]
	s_or_b32 s74, s16, 32
	s_ashr_i32 s75, s74, 31
	s_or_b32 s16, s16, 48
	s_lshl_b64 s[74:75], s[74:75], 8
	s_ashr_i32 s17, s16, 31
	global_load_dwordx4 v[146:149], v[204:205], off
	global_load_dwordx4 v[150:153], v[206:207], off
	v_lshl_add_u64 v[204:205], v[170:171], 0, s[74:75]
	s_lshl_b64 s[16:17], s[16:17], 8
	v_lshl_add_u64 v[206:207], v[170:171], 0, s[16:17]
	global_load_dwordx4 v[154:157], v[204:205], off
	global_load_dwordx4 v[158:161], v[206:207], off

; template <int R> __device__ __forceinline__ void bias_r(f32x16& p0, f32x16& p1, float dq, float nslope) {
;   constexpr int C0 = (R & 3) + 8 * (R >> 2);
;   float x0, x1, a0 = p0[R], a1 = p1[R];
;   asm("v_sub_f32_e32 %0, %1, %2" : "=v"(x0) : "n"(__builtin_bit_cast(int, (float)C0)), "v"(dq));
;   asm("v_sub_f32_e32 %0, %1, %2" : "=v"(x1) : "n"(__builtin_bit_cast(int, (float)(C0 + 32))), "v"(dq));
;   asm("v_fma_f32 %0, %1, |%2|, %0" : "+v"(a0) : "v"(nslope), "v"(x0));
;   asm("v_fma_f32 %0, %1, |%2|, %0" : "+v"(a1) : "v"(nslope), "v"(x1));
;   p0[R] = a0; p1[R] = a1;
;   if constexpr (R < 15) bias_r<R + 1>(p0, p1, dq, nslope);
; }
.LBB0_375:
.LBB0_379:
	s_waitcnt lgkmcnt(0)
	s_barrier
	ds_read_b128 v[114:117], v195 offset:49152
	ds_read_b128 v[204:207], v195 offset:57344
	s_andn2_b64 vcc, exec, s[14:15]
	s_waitcnt lgkmcnt(1)
	v_mfma_f32_32x32x16_bf16 v[98:113], v[114:117], v[130:133], v[82:97]
	s_waitcnt lgkmcnt(0)
	v_mfma_f32_32x32x16_bf16 v[114:129], v[204:207], v[130:133], v[82:97]
	ds_read_b128 v[204:207], v196 offset:49152
	s_waitcnt lgkmcnt(0)
	v_mfma_f32_32x32x16_bf16 v[98:113], v[204:207], v[134:137], v[98:113]
	ds_read_b128 v[204:207], v196 offset:57344
	s_waitcnt lgkmcnt(0)
	v_mfma_f32_32x32x16_bf16 v[114:129], v[204:207], v[134:137], v[114:129]
	ds_read_b128 v[204:207], v197 offset:49152
	s_waitcnt lgkmcnt(0)
	v_mfma_f32_32x32x16_bf16 v[98:113], v[204:207], v[138:141], v[98:113]
	ds_read_b128 v[204:207], v197 offset:57344
	s_waitcnt lgkmcnt(0)
	v_mfma_f32_32x32x16_bf16 v[114:129], v[204:207], v[138:141], v[114:129]
	ds_read_b128 v[204:207], v198 offset:49152
	s_waitcnt lgkmcnt(0)
	v_mfma_f32_32x32x16_bf16 v[98:113], v[204:207], v[142:145], v[98:113]
	ds_read_b128 v[204:207], v198 offset:57344
	s_waitcnt lgkmcnt(0)
	v_mfma_f32_32x32x16_bf16 v[114:129], v[204:207], v[142:145], v[114:129]
	s_cbranch_vccnz .LBB0_381
	s_add_i32 s46, s47, -1
	s_add_i32 s72, s72, 1
	s_add_i32 s14, s39, -1
	s_cmp_lt_i32 s46, s23
	s_cselect_b32 s14, s72, s14
	s_lshl_b32 s14, s14, 6
	v_cvt_f32_i32_e32 v0, s14
	v_sub_f32_e32 v0, v192, v0
	ds_read_b64_tr_b16 v[204:205], v193 offset:0
	ds_read_b64_tr_b16 v[206:207], v193 offset:0x800
	ds_read_b64_tr_b16 v[208:209], v193 offset:0x1000
	ds_read_b64_tr_b16 v[210:211], v193 offset:0x1800
	ds_read_b64_tr_b16 v[212:213], v193 offset:0x2000
	ds_read_b64_tr_b16 v[214:215], v193 offset:0x2800
	ds_read_b64_tr_b16 v[216:217], v193 offset:0x3000
	ds_read_b64_tr_b16 v[218:219], v193 offset:0x3800
	s_waitcnt lgkmcnt(0)
	s_nop 0
	v_mfma_f32_32x32x16_bf16 v[64:79], v[2:5], v[204:207], v[64:79]
	v_sub_f32_e32 v14, 0, v0
	v_sub_f32_e32 v15, 0x42000000, v0
	v_fma_f32 v98, v81, |v14|, v98
	v_sub_f32_e32 v14, 0x3f800000, v0
	ds_read_b64_tr_b16 v[204:205], v193 offset:0x200
	ds_read_b64_tr_b16 v[206:207], v193 offset:0xa00
	v_mfma_f32_32x32x16_bf16 v[64:79], v[6:9], v[208:211], v[64:79]
	v_fma_f32 v114, v81, |v15|, v114
	v_sub_f32_e32 v15, 0x42040000, v0
	v_fma_f32 v99, v81, |v14|, v99
	v_sub_f32_e32 v14, 0x40000000, v0
	ds_read_b64_tr_b16 v[208:209], v193 offset:0x1200
	ds_read_b64_tr_b16 v[210:211], v193 offset:0x1a00
	v_mfma_f32_32x32x16_bf16 v[64:79], v[10:13], v[212:215], v[64:79]
	v_fma_f32 v115, v81, |v15|, v115
	v_sub_f32_e32 v15, 0x42080000, v0
	v_fma_f32 v100, v81, |v14|, v100
	v_sub_f32_e32 v14, 0x40400000, v0
	ds_read_b64_tr_b16 v[212:213], v193 offset:0x2200
	ds_read_b64_tr_b16 v[214:215], v193 offset:0x2a00
	ds_read_b64_tr_b16 v[220:221], v193 offset:0x3200
	ds_read_b64_tr_b16 v[222:223], v193 offset:0x3a00
	s_waitcnt lgkmcnt(0)
	v_mfma_f32_32x32x16_bf16 v[64:79], v[162:165], v[216:219], v[64:79]
	v_fma_f32 v116, v81, |v15|, v116
	v_sub_f32_e32 v15, 0x420c0000, v0
	v_fma_f32 v101, v81, |v14|, v101
	v_sub_f32_e32 v14, 0x41000000, v0
	v_mfma_f32_32x32x16_bf16 v[48:63], v[2:5], v[204:207], v[48:63]
	v_fma_f32 v117, v81, |v15|, v117
	v_sub_f32_e32 v15, 0x42200000, v0
	v_fma_f32 v102, v81, |v14|, v102
	v_sub_f32_e32 v14, 0x41100000, v0
	ds_read_b64_tr_b16 v[204:205], v193 offset:0x400
	ds_read_b64_tr_b16 v[206:207], v193 offset:0xc00
	v_mfma_f32_32x32x16_bf16 v[48:63], v[6:9], v[208:211], v[48:63]
	v_fma_f32 v118, v81, |v15|, v118
	v_sub_f32_e32 v15, 0x42240000, v0
	v_fma_f32 v103, v81, |v14|, v103
	v_sub_f32_e32 v14, 0x41200000, v0
	ds_read_b64_tr_b16 v[208:209], v193 offset:0x1400
	ds_read_b64_tr_b16 v[210:211], v193 offset:0x1c00
	v_mfma_f32_32x32x16_bf16 v[48:63], v[10:13], v[212:215], v[48:63]
	v_fma_f32 v119, v81, |v15|, v119
	v_sub_f32_e32 v15, 0x42280000, v0
	v_fma_f32 v104, v81, |v14|, v104
	v_sub_f32_e32 v14, 0x41300000, v0
	ds_read_b64_tr_b16 v[212:213], v193 offset:0x2400
	ds_read_b64_tr_b16 v[214:215], v193 offset:0x2c00
	ds_read_b64_tr_b16 v[216:217], v193 offset:0x3400
	ds_read_b64_tr_b16 v[218:219], v193 offset:0x3c00
	s_waitcnt lgkmcnt(0)
	v_mfma_f32_32x32x16_bf16 v[48:63], v[162:165], v[220:223], v[48:63]
	v_fma_f32 v120, v81, |v15|, v120
	v_sub_f32_e32 v15, 0x422c0000, v0
	v_fma_f32 v105, v81, |v14|, v105
	v_sub_f32_e32 v14, 0x41800000, v0
	v_mfma_f32_32x32x16_bf16 v[32:47], v[2:5], v[204:207], v[32:47]
	v_fma_f32 v121, v81, |v15|, v121
	v_sub_f32_e32 v15, 0x42400000, v0
	v_fma_f32 v106, v81, |v14|, v106
	v_sub_f32_e32 v14, 0x41880000, v0
	ds_read_b64_tr_b16 v[204:205], v193 offset:0x600
	ds_read_b64_tr_b16 v[206:207], v193 offset:0xe00
	v_mfma_f32_32x32x16_bf16 v[32:47], v[6:9], v[208:211], v[32:47]
	v_fma_f32 v122, v81, |v15|, v122
	v_sub_f32_e32 v15, 0x42440000, v0
	v_fma_f32 v107, v81, |v14|, v107
	v_sub_f32_e32 v14, 0x41900000, v0
	ds_read_b64_tr_b16 v[208:209], v193 offset:0x1600
	ds_read_b64_tr_b16 v[210:211], v193 offset:0x1e00
	v_mfma_f32_32x32x16_bf16 v[32:47], v[10:13], v[212:215], v[32:47]
	v_fma_f32 v123, v81, |v15|, v123
	v_sub_f32_e32 v15, 0x42480000, v0
	v_fma_f32 v108, v81, |v14|, v108
	v_sub_f32_e32 v14, 0x41980000, v0
	ds_read_b64_tr_b16 v[212:213], v193 offset:0x2600
	ds_read_b64_tr_b16 v[214:215], v193 offset:0x2e00
	ds_read_b64_tr_b16 v[220:221], v193 offset:0x3600
	ds_read_b64_tr_b16 v[222:223], v193 offset:0x3e00
	s_waitcnt lgkmcnt(0)
	v_mfma_f32_32x32x16_bf16 v[32:47], v[162:165], v[216:219], v[32:47]
	v_fma_f32 v124, v81, |v15|, v124
	v_sub_f32_e32 v15, 0x424c0000, v0
	v_fma_f32 v109, v81, |v14|, v109
	v_sub_f32_e32 v14, 0x41c00000, v0
	v_mfma_f32_32x32x16_bf16 v[16:31], v[2:5], v[204:207], v[16:31]
	v_fma_f32 v125, v81, |v15|, v125
	v_sub_f32_e32 v15, 0x42600000, v0
	v_fma_f32 v110, v81, |v14|, v110
	v_sub_f32_e32 v14, 0x41c80000, v0
	v_mfma_f32_32x32x16_bf16 v[16:31], v[6:9], v[208:211], v[16:31]
	v_fma_f32 v126, v81, |v15|, v126
	v_sub_f32_e32 v15, 0x42640000, v0
	v_fma_f32 v111, v81, |v14|, v111
	v_sub_f32_e32 v14, 0x41d00000, v0
	v_mfma_f32_32x32x16_bf16 v[16:31], v[10:13], v[212:215], v[16:31]
	v_fma_f32 v127, v81, |v15|, v127
	v_sub_f32_e32 v15, 0x42680000, v0
	v_fma_f32 v112, v81, |v14|, v112
	v_sub_f32_e32 v14, 0x41d80000, v0
	v_mfma_f32_32x32x16_bf16 v[16:31], v[162:165], v[220:223], v[16:31]
	v_sub_f32_e32 v0, 0x426c0000, v0
	v_fma_f32 v128, v81, |v15|, v128
	v_fma_f32 v113, v81, |v14|, v113
	v_fma_f32 v129, v81, |v0|, v129
	s_barrier
	s_branch .Lafter_bias_1
; template <int R> __device__ __forceinline__ void bias_r(f32x16& p0, f32x16& p1, float dq, float nslope) {
;   constexpr int C0 = (R & 3) + 8 * (R >> 2);
;   float x0, x1, a0 = p0[R], a1 = p1[R];
;   asm("v_sub_f32_e32 %0, %1, %2" : "=v"(x0) : "n"(__builtin_bit_cast(int, (float)C0)), "v"(dq));
;   asm("v_sub_f32_e32 %0, %1, %2" : "=v"(x1) : "n"(__builtin_bit_cast(int, (float)(C0 + 32))), "v"(dq));
;   asm("v_fma_f32 %0, %1, |%2|, %0" : "+v"(a0) : "v"(nslope), "v"(x0));
;   asm("v_fma_f32 %0, %1, |%2|, %0" : "+v"(a1) : "v"(nslope), "v"(x1));
;   p0[R] = a0; p1[R] = a1;
;   if constexpr (R < 15) bias_r<R + 1>(p0, p1, dq, nslope);
; }
.LBB0_381:
	s_add_i32 s46, s47, -1
	s_add_i32 s72, s72, 1
	s_add_i32 s14, s39, -1
	s_cmp_lt_i32 s46, s23
	s_cselect_b32 s14, s72, s14
	s_lshl_b32 s14, s14, 6
	v_cvt_f32_i32_e32 v0, s14
	s_barrier
	v_sub_f32_e32 v0, v192, v0
	v_sub_f32_e32 v14, 0, v0
	v_sub_f32_e32 v15, 0x42000000, v0
	s_nop 0
	v_fma_f32 v98, v81, |v14|, v98
	v_sub_f32_e32 v14, 0x3f800000, v0
	v_fma_f32 v114, v81, |v15|, v114
	v_sub_f32_e32 v15, 0x42040000, v0
	s_nop 0
	v_fma_f32 v99, v81, |v14|, v99
	v_sub_f32_e32 v14, 0x40000000, v0
	v_fma_f32 v115, v81, |v15|, v115
	v_sub_f32_e32 v15, 0x42080000, v0
	s_nop 0
	v_fma_f32 v100, v81, |v14|, v100
	v_sub_f32_e32 v14, 0x40400000, v0
	v_fma_f32 v116, v81, |v15|, v116
	v_sub_f32_e32 v15, 0x420c0000, v0
	s_nop 0
	v_fma_f32 v101, v81, |v14|, v101
	v_sub_f32_e32 v14, 0x41000000, v0
	v_fma_f32 v117, v81, |v15|, v117
	v_sub_f32_e32 v15, 0x42200000, v0
	s_nop 0
	v_fma_f32 v102, v81, |v14|, v102
	v_sub_f32_e32 v14, 0x41100000, v0
	v_fma_f32 v118, v81, |v15|, v118
	v_sub_f32_e32 v15, 0x42240000, v0
	s_nop 0
	v_fma_f32 v103, v81, |v14|, v103
	v_sub_f32_e32 v14, 0x41200000, v0
	v_fma_f32 v119, v81, |v15|, v119
	v_sub_f32_e32 v15, 0x42280000, v0
	s_nop 0
	v_fma_f32 v104, v81, |v14|, v104
	v_sub_f32_e32 v14, 0x41300000, v0
	v_fma_f32 v120, v81, |v15|, v120
	v_sub_f32_e32 v15, 0x422c0000, v0
	s_nop 0
	v_fma_f32 v105, v81, |v14|, v105
	v_sub_f32_e32 v14, 0x41800000, v0
	v_fma_f32 v121, v81, |v15|, v121
	v_sub_f32_e32 v15, 0x42400000, v0
	s_nop 0
	v_fma_f32 v106, v81, |v14|, v106
	v_sub_f32_e32 v14, 0x41880000, v0
	v_fma_f32 v122, v81, |v15|, v122
	v_sub_f32_e32 v15, 0x42440000, v0
	s_nop 0
	v_fma_f32 v107, v81, |v14|, v107
	v_sub_f32_e32 v14, 0x41900000, v0
	v_fma_f32 v123, v81, |v15|, v123
	v_sub_f32_e32 v15, 0x42480000, v0
	s_nop 0
	v_fma_f32 v108, v81, |v14|, v108
	v_sub_f32_e32 v14, 0x41980000, v0
	v_fma_f32 v124, v81, |v15|, v124
	v_sub_f32_e32 v15, 0x424c0000, v0
	s_nop 0
	v_fma_f32 v109, v81, |v14|, v109
	v_sub_f32_e32 v14, 0x41c00000, v0
	v_fma_f32 v125, v81, |v15|, v125
	v_sub_f32_e32 v15, 0x42600000, v0
	s_nop 0
	v_fma_f32 v110, v81, |v14|, v110
	v_sub_f32_e32 v14, 0x41c80000, v0
	v_fma_f32 v126, v81, |v15|, v126
	v_sub_f32_e32 v15, 0x42640000, v0
	s_nop 0
	v_fma_f32 v111, v81, |v14|, v111
	v_sub_f32_e32 v14, 0x41d00000, v0
	v_fma_f32 v127, v81, |v15|, v127
	v_sub_f32_e32 v15, 0x42680000, v0
	s_nop 0
	v_fma_f32 v112, v81, |v14|, v112
	v_sub_f32_e32 v14, 0x41d80000, v0
	v_sub_f32_e32 v0, 0x426c0000, v0
	v_fma_f32 v128, v81, |v15|, v128
	s_nop 0
	v_fma_f32 v113, v81, |v14|, v113
	v_fma_f32 v129, v81, |v0|, v129
.Lafter_bias_1:
	s_add_i32 s33, s46, 2
	s_and_b64 s[16:17], exec, s[12:13]
	s_cselect_b32 s16, s46, s33
	s_cmp_gt_i32 s16, s11
	s_cbranch_scc1 .Lstg1_mid
	s_waitcnt vmcnt(3)
	ds_write_b128 v199, v[146:149] offset:16384
	s_waitcnt vmcnt(2)
	ds_write_b128 v200, v[150:153] offset:20480
	s_waitcnt vmcnt(1)
	ds_write_b128 v201, v[154:157] offset:24576
	s_waitcnt vmcnt(0)
	ds_write_b128 v202, v[158:161] offset:28672
.Lstg1_mid:
	s_cmp_ge_i32 s16, s11
	s_cbranch_scc1 .Lstg1_end
	s_add_i32 s17, s16, 1
	s_not_b32 s16, s16
	s_add_i32 s33, s17, s22
	s_add_i32 s16, s38, s16
	s_cmp_lt_i32 s17, s23
	s_cselect_b32 s16, s33, s16
	s_lshl_b32 s16, s16, 6
	s_ashr_i32 s17, s16, 31
	s_lshl_b64 s[72:73], s[16:17], 8
	v_lshl_add_u64 v[204:205], v[170:171], 0, s[72:73]
	s_or_b32 s72, s16, 16
	s_ashr_i32 s73, s72, 31
	s_lshl_b64 s[72:73], s[72:73], 8
	v_lshl_add_u64 v[206:207], v[170:171], 0, s[72:73]
	s_or_b32 s72, s16, 32
	s_ashr_i32 s73, s72, 31
	s_or_b32 s16, s16, 48
	s_lshl_b64 s[72:73], s[72:73], 8
	s_ashr_i32 s17, s16, 31
	global_load_dwordx4 v[146:149], v[204:205], off
	global_load_dwordx4 v[150:153], v[206:207], off
	v_lshl_add_u64 v[204:205], v[170:171], 0, s[72:73]
	s_lshl_b64 s[16:17], s[16:17], 8
	v_lshl_add_u64 v[206:207], v[170:171], 0, s[16:17]
	global_load_dwordx4 v[154:157], v[204:205], off
	global_load_dwordx4 v[158:161], v[206:207], off

; __device__ __forceinline__ void attn_unit_pp(int b, int h, int qb, int par, const bf16_t* __restrict__ QBp, const bf16_t* __restrict__ KBp, const bf16_t* __restrict__ VBp, ...
;     ...
;   _Pragma("nounroll") for (int j = 0; j < n; j += 2) { PP_STEP(j, 0); PP_STEP(j + 1, 1); }
.LBB0_389:
.LBB0_393:
	s_xor_b64 s[14:15], s[14:15], -1
	s_add_i32 s39, s39, -2
	s_cmp_gt_i32 s47, s11
	s_waitcnt lgkmcnt(0)
	s_barrier
	s_cbranch_scc1 .LBB0_403
	s_mov_b32 s46, s47
	s_branch .LBB0_364
